# hg_scan: static priority raise for the four waves that carry the output work (critical path), inline nop pairs dropped
# baseline (speedup 1.0000x reference)
.LBB0_330:
	s_or_b64 exec, exec, s[0:1]
	s_add_i32 s33, 0, 0x23fa0
	s_mov_b32 s0, -1
	v_mov_b32_e32 v0, s33
	s_barrier
	s_cmp_lt_u32 s79, 4
	s_cbranch_scc0 .Lhs_noprio
	s_setprio 2
	s_nop 0
.Lhs_noprio:
	ds_read_b128 v[0:3], v0
	s_mov_b32 s45, -1
	s_mov_b32 s31, 0
	s_andn2_b64 vcc, exec, s[8:9]
	s_waitcnt lgkmcnt(0)
	v_readfirstlane_b32 s34, v0
	v_cndmask_b32_e64 v0, 0, 1, s[8:9]
	v_readfirstlane_b32 s35, v1
	v_readfirstlane_b32 s2, v2
	v_cmp_ne_u32_e64 s[72:73], 1, v0
	v_readfirstlane_b32 s3, v3
	s_cbranch_vccnz .LBB0_361
	s_add_u32 s42, s2, 0x4800000
	s_addc_u32 s43, s3, 0
	s_add_u32 s24, s2, 0x2800000
	v_mbcnt_lo_u32_b32 v0, s0, 0
	s_addc_u32 s25, s3, 0
	v_mbcnt_hi_u32_b32 v5, s0, v0
	v_readlane_b32 s0, v247, 1
	s_add_u32 s44, s2, 0x3800000
	s_addc_u32 s46, s3, 0
	v_add_u32_e32 v6, s0, v5
	v_lshlrev_b32_e32 v2, 2, v6
	s_add_u32 s26, s2, 0xe500000
	v_ashrrev_i32_e32 v3, 31, v2
	s_addc_u32 s27, s3, 0
	v_lshl_add_u64 v[2:3], v[2:3], 2, s[2:3]
	s_mov_b64 s[2:3], 0xf580000
	v_and_b32_e32 v64, 15, v5
	v_lshl_add_u64 v[38:39], v[2:3], 0, s[2:3]
	s_add_i32 s2, 0, 0x10500
	v_ashrrev_i32_e32 v4, 4, v6
	s_movk_i32 s0, 0x1c00
	v_lshlrev_b32_e32 v0, 3, v64
	s_movk_i32 s36, 0x110
	s_movk_i32 s37, 0x90
	v_mov_b32_e32 v12, s2
	v_lshrrev_b32_e32 v13, 2, v5
	v_mul_lo_u32 v7, v4, s0
	v_lshl_or_b32 v0, v4, 7, v0
	v_mul_lo_u32 v10, v4, s36
	v_mad_u32_u24 v66, v64, s37, v12
	v_lshlrev_b32_e32 v12, 2, v4
	s_lshl_b32 s2, s79, 4
	v_and_b32_e32 v4, 28, v13
	v_add_u32_e32 v14, s2, v4
	v_lshlrev_b32_e32 v15, 2, v14
	s_add_i32 s3, 0, 0x11600
	v_add_u32_e32 v67, s3, v15
	s_add_i32 s3, 0, 0x11c00
	v_mov_b32_e32 v16, s3
	s_lshl_b32 s3, s79, 1
	s_lshr_b32 s38, s75, 7
	s_and_b32 s39, s3, 2
	s_lshl_b32 s3, s38, 4
	s_cmpk_lt_u32 s75, 0x100
	s_cselect_b64 s[28:29], -1, 0
	s_and_b32 s30, s2, 48
	v_or_b32_e32 v21, s2, v64
	s_add_i32 s2, 0, 0x11800
	v_add_u32_e32 v71, s2, v15
	s_add_i32 s2, 0, 0x11a00
	s_cmp_lt_u32 s39, s38
	v_or_b32_e32 v22, 1, v4
	s_cselect_b64 s[12:13], -1, 0
	s_cmp_eq_u32 s39, s38
	v_cmp_ge_i32_e64 s[6:7], v22, v64
	v_or_b32_e32 v22, 2, v4
	v_or_b32_e32 v13, 3, v13
	v_and_b32_e32 v9, 7, v5
	v_mad_u32_u24 v68, v64, s36, v16
	v_or_b32_e32 v16, s3, v64
	v_and_b32_e32 v69, -16, v5
	v_and_b32_e32 v17, 1, v5
	v_add_u32_e32 v18, s3, v4
	v_lshlrev_b32_e32 v5, 1, v5
	v_add_u32_e32 v72, s2, v15
	s_cselect_b64 s[2:3], -1, 0
	v_cmp_ge_i32_e32 vcc, v4, v64
	v_cmp_ge_i32_e64 s[8:9], v22, v64
	v_cmp_ge_i32_e64 s[10:11], v13, v64
	v_and_b32_e32 v5, 28, v5
	s_and_b64 s[14:15], s[2:3], vcc
	s_and_b64 s[16:17], s[2:3], s[6:7]
	s_and_b64 s[18:19], s[2:3], s[8:9]
	s_and_b64 s[20:21], s[2:3], s[10:11]
	s_or_b32 s47, s39, 1
	v_ashrrev_i32_e32 v8, 3, v6
	v_lshlrev_b32_e32 v1, 3, v9
	v_add_u32_e32 v19, 0, v5
	v_or_b32_e32 v5, s30, v64
	v_lshl_or_b32 v15, s39, 4, v64
	v_cmp_eq_u32_e64 s[2:3], 0, v17
	v_cmp_eq_u32_e64 s[4:5], 1, v17
	v_mul_lo_u32 v17, v18, s37
	v_lshl_or_b32 v18, s47, 4, v64
	s_cmp_lt_u32 s47, s38
	v_lshl_or_b32 v36, v8, 6, v1
	v_mul_lo_u32 v8, v8, s37
	v_mul_lo_u32 v16, v16, s36
	v_mad_u32_u24 v70, v5, s36, 0
	v_mul_lo_u32 v21, v21, s37
	v_mad_u32_u24 v15, v15, s36, 0
	v_mad_u32_u24 v18, v18, s36, 0
	s_cselect_b64 s[36:37], -1, 0
	s_cmp_eq_u32 s47, s38
	v_lshl_add_u32 v13, s39, 5, v19
	s_cselect_b64 s[38:39], -1, 0
	v_mov_b32_e32 v1, 0
	s_movk_i32 s0, 0x60
	v_lshlrev_b32_e32 v5, 7, v5
	s_and_b64 s[40:41], s[38:39], vcc
	s_and_b64 s[48:49], s[38:39], s[6:7]
	s_and_b64 s[52:53], s[38:39], s[8:9]
	s_and_b64 s[38:39], s[38:39], s[10:11]
	v_cmp_gt_i32_e64 s[0:1], s0, v6
	v_lshlrev_b32_e32 v6, 4, v6
	v_sub_u32_e32 v20, v70, v5
	v_mov_b32_e32 v5, v1
	s_or_b64 s[6:7], s[12:13], s[14:15]
	s_or_b64 s[8:9], s[12:13], s[16:17]
	s_or_b64 s[10:11], s[12:13], s[18:19]
	s_or_b64 s[12:13], s[12:13], s[20:21]
	s_or_b64 s[14:15], s[36:37], s[40:41]
	s_or_b64 s[16:17], s[36:37], s[48:49]
	s_or_b64 s[18:19], s[36:37], s[52:53]
	s_or_b64 s[20:21], s[36:37], s[38:39]
	s_mov_b64 s[36:37], 0xf580600
	v_add_u32_e32 v65, 0x400, v7
	v_mov_b32_e32 v37, v1
	v_add_u32_e32 v10, 0, v10
	v_lshlrev_b32_e32 v11, 4, v64
	v_add_u32_e32 v8, 0, v8
	v_lshlrev_b32_e32 v9, 4, v9
	v_lshlrev_b32_e32 v14, 1, v14
	v_add_u32_e32 v16, 0, v16
	v_add_u32_e32 v21, 0, v21
	v_lshl_add_u32 v19, s47, 5, v19
	v_or_b32_e32 v7, v7, v64
	v_lshl_add_u64 v[40:41], v[2:3], 0, s[36:37]
	v_lshl_add_u64 v[44:45], v[0:1], 1, s[24:25]
	v_lshlrev_b32_e32 v2, 2, v64
	v_mov_b32_e32 v3, v1
	v_lshl_add_u64 v[48:49], s[30:31], 0, v[4:5]
	v_lshlrev_b64 v[50:51], 1, v[0:1]
	v_add_u32_e32 v0, 0, v6
	v_add_u32_e32 v73, 0x39200, v7
	s_lshl_b32 s47, s80, 2
	s_lshl_b32 s48, s76, 2
	v_lshl_add_u64 v[42:43], v[36:37], 1, s[26:27]
	v_lshl_add_u64 v[46:47], s[34:35], 0, v[2:3]
	s_movk_i32 s49, 0x2000
	v_add_u32_e32 v49, v10, v11
	v_add_u32_e32 v74, v8, v9
	v_add_u32_e32 v75, 0x11600, v0
	v_add_u32_e32 v76, v66, v12
	s_movk_i32 s51, 0x7fff
	s_mov_b32 s52, 0xffff0000
	v_add_u32_e32 v77, v68, v14
	v_add_u32_e32 v78, v15, v69
	v_add_u32_e32 v79, v18, v69
	v_add_u32_e32 v80, v20, v69
	v_add_u32_e32 v81, v21, v69
	s_mov_b64 s[30:31], 0x600
	s_mov_b64 s[34:35], 0x1000
	v_mov_b32_e32 v82, 0x600
	v_mov_b32_e32 v83, 1
	v_add_u32_e32 v84, v16, v69
	v_add_u32_e32 v85, v13, v17
	v_add_u32_e32 v86, v19, v17
	s_mov_b32 s53, s80
	s_branch .LBB0_333

.LBB0_361:
	s_setprio 0
	s_nop 0
	s_waitcnt vmcnt(1)
	v_mov_b32_e32 v0, s33
	s_barrier
	s_waitcnt vmcnt(0)
	ds_read_b128 v[0:3], v0
	s_cmpk_gt_i32 s80, 0x7f
	v_writelane_b32 v247, s72, 21
	s_waitcnt lgkmcnt(0)
	v_readfirstlane_b32 s0, v2
	v_readfirstlane_b32 s2, v3
	v_readfirstlane_b32 s1, v0
	v_readfirstlane_b32 s5, v1
	v_writelane_b32 v247, s73, 22
	s_cbranch_scc1 .Ltail2_p0b
	v_mbcnt_lo_u32_b32 v0, s45, 0
	v_mbcnt_hi_u32_b32 v16, s45, v0
	v_readlane_b32 s14, v247, 11
	s_add_u32 s33, s0, 0xc800000
	s_addc_u32 s42, s2, 0
	v_lshl_add_u32 v1, v16, 4, s14
	v_add_u32_e32 v0, 0x2000, v1
	v_ashrrev_i32_e32 v2, 31, v0
	v_lshrrev_b32_e32 v2, 22, v2
	v_add_u32_e32 v2, v0, v2
	v_ashrrev_i32_e32 v2, 10, v2
	v_mul_i32_i24_e32 v4, 0x400, v2
	v_sub_u32_e32 v0, v0, v4
	v_lshrrev_b32_e32 v4, 4, v0
	v_bitop3_b32 v0, v4, v0, 32 bitop3:0x6c
	v_ashrrev_i32_e32 v4, 31, v0
	v_lshrrev_b32_e32 v4, 26, v4
	v_add_u32_e32 v4, v0, v4
	v_ashrrev_i32_e32 v5, 6, v4
	v_and_b32_e32 v4, 0xffc0, v4
	v_sub_u32_e32 v0, v0, v4
	v_lshrrev_b16_e32 v4, 7, v0
	s_add_u32 s43, s0, 0x1a00000
	v_lshlrev_b32_e32 v3, 5, v2
	v_and_b32_e32 v4, 1, v4
	v_lshlrev_b32_e32 v2, 3, v2
	s_addc_u32 s44, s2, 0
	v_add_u16_e32 v0, v0, v4
	v_mov_b32_e32 v4, 1
	v_and_b32_e32 v2, -16, v2
	s_ashr_i32 s81, s80, 31
	v_and_b32_e32 v3, 32, v3
	v_ashrrev_i16_sdwa v0, v4, sext(v0) dst_sel:DWORD dst_unused:UNUSED_PAD src0_sel:DWORD src1_sel:BYTE_0
	v_add_u32_e32 v2, v5, v2
	s_lshr_b32 s0, s81, 26
	v_add_u32_sdwa v0, v3, sext(v0) dst_sel:DWORD dst_unused:UNUSED_PAD src0_sel:DWORD src1_sel:WORD_0
	v_lshlrev_b32_e32 v3, 12, v2
	s_add_i32 s0, s80, s0
	v_lshl_add_u32 v0, v0, 1, v3
	v_ashrrev_i32_e32 v3, 31, v1
	s_ashr_i32 s2, s0, 6
	s_and_b32 s0, s0, 0xffc0
	v_lshrrev_b32_e32 v3, 22, v3
	s_sub_i32 s3, s80, s0
	v_add_u32_e32 v3, v1, v3
	s_bfe_i32 s0, s3, 0x80000
	v_ashrrev_i32_e32 v3, 10, v3
	s_bfe_u32 s0, s0, 0x3000c
	v_mul_i32_i24_e32 v6, 0x400, v3
	s_add_i32 s4, s3, s0
	v_sub_u32_e32 v1, v1, v6
	s_bfe_i32 s0, s4, 0x80000
	v_lshrrev_b32_e32 v6, 4, v1
	s_sext_i32_i16 s0, s0
	s_and_b32 s4, s4, 0xfff8
	v_bitop3_b32 v1, v6, v1, 32 bitop3:0x6c
	s_lshr_b32 s0, s0, 3
	s_sub_i32 s4, s3, s4
	s_add_i32 s3, s80, 63
	v_ashrrev_i32_e32 v6, 31, v1
	s_cmpk_lt_u32 s3, 0x7f
	v_lshrrev_b32_e32 v6, 26, v6
	s_cselect_b32 s12, 0, 0x500000
	s_bfe_i64 s[6:7], s[0:1], 0x100000
	s_bfe_i64 s[8:9], s[4:5], 0x80000
	s_ashr_i32 s3, s2, 31
	v_add_u32_e32 v6, v1, v6
	s_lshl_b64 s[6:7], s[6:7], 19
	s_lshl_b64 s[8:9], s[8:9], 9
	s_lshl_b64 s[10:11], s[2:3], 20
	v_lshlrev_b32_e32 v5, 5, v3
	v_ashrrev_i32_e32 v7, 6, v6
	v_and_b32_e32 v6, 0xc0, v6
	v_lshlrev_b32_e32 v3, 3, v3
	s_add_u32 s3, s43, s8
	v_sub_u32_e32 v1, v1, v6
	v_and_b32_e32 v3, -16, v3
	s_addc_u32 s13, s44, s9
	v_and_b32_e32 v5, 32, v5
	v_ashrrev_i16_sdwa v1, v4, sext(v1) dst_sel:DWORD dst_unused:UNUSED_PAD src0_sel:DWORD src1_sel:BYTE_0
	v_add_u32_e32 v3, v7, v3
	s_add_u32 s38, s3, s10
	v_add_u32_sdwa v1, v5, sext(v1) dst_sel:DWORD dst_unused:UNUSED_PAD src0_sel:DWORD src1_sel:WORD_0
	v_lshlrev_b32_e32 v4, 12, v3
	s_addc_u32 s39, s13, s11
	s_add_i32 s45, s14, 0
	v_lshl_add_u32 v4, v1, 1, v4
	s_add_i32 m0, s45, 0x10000
	v_lshlrev_b32_e32 v1, 11, v3
	global_load_lds_dwordx4 v4, s[38:39]
	s_add_i32 m0, s45, 0x12000
	s_add_u32 s10, s38, 0x80000
	global_load_lds_dwordx4 v0, s[38:39]
	s_addc_u32 s11, s39, 0
	s_add_i32 m0, s45, 0x14000
	v_lshlrev_b32_e32 v2, 11, v2
	global_load_lds_dwordx4 v4, s[10:11]
	s_add_i32 m0, s45, 0x16000
	s_add_u32 s3, s33, s8
	s_addc_u32 s8, s42, s9
	s_add_u32 s3, s3, s6
	s_addc_u32 s6, s8, s7
	s_add_u32 s36, s3, s12
	s_addc_u32 s37, s6, 0
	s_add_i32 s46, s45, 0x2000
	v_sub_u32_e32 v6, v4, v1
	global_load_lds_dwordx4 v0, s[10:11]
	s_mov_b32 m0, s45
	s_add_u32 s6, s36, 0x40000
	v_sub_u32_e32 v2, v0, v2
	global_load_lds_dwordx4 v6, s[36:37]
	s_mov_b32 m0, s46
	s_addc_u32 s7, s37, 0
	s_add_i32 s47, s45, 0x4000
	global_load_lds_dwordx4 v2, s[36:37]
	s_mov_b32 m0, s47
	s_add_i32 s48, s45, 0x6000
	global_load_lds_dwordx4 v6, s[6:7]
	s_mov_b32 m0, s48
	v_mov_b32_e32 v5, 0
	global_load_lds_dwordx4 v2, s[6:7]
	v_mov_b32_e32 v1, v5
	v_mov_b32_e32 v7, v5
	v_mov_b32_e32 v3, v5
	v_readlane_b32 s3, v247, 7
	v_lshl_add_u64 v[14:15], s[38:39], 0, v[4:5]
	v_lshl_add_u64 v[12:13], s[38:39], 0, v[0:1]
	v_lshl_add_u64 v[8:9], s[36:37], 0, v[6:7]
	s_cmp_lg_u32 s3, 1
	v_lshl_add_u64 v[10:11], s[36:37], 0, v[2:3]
	s_cbranch_scc1 .LBB0_364
	s_barrier
.LBB0_364:
	s_sext_i32_i8 s3, s4
	s_lshl_b32 s2, s2, 3
	s_add_i32 s6, s2, s3
	s_add_u32 s49, s1, 0x2000000
	s_addc_u32 s51, s5, 0
	s_mov_b64 s[4:5], 0x80
	s_add_i32 m0, s45, 0x18000
	v_lshl_add_u64 v[14:15], v[14:15], 0, s[4:5]
	s_waitcnt vmcnt(2)
	s_barrier
	global_load_lds_dwordx4 v[14:15], off
	v_lshl_add_u64 v[12:13], v[12:13], 0, s[4:5]
	s_add_i32 m0, s45, 0x1a000
	s_add_i32 s52, s45, 0x8000
	s_add_i32 s53, s45, 0xa000
	global_load_lds_dwordx4 v[12:13], off
	v_lshl_add_u64 v[8:9], v[8:9], 0, s[4:5]
	s_mov_b32 m0, s52
	s_add_u32 s2, s38, 0x80080
	global_load_lds_dwordx4 v[8:9], off
	v_lshl_add_u64 v[8:9], v[10:11], 0, s[4:5]
	s_mov_b32 m0, s53
	s_addc_u32 s3, s39, 0
	global_load_lds_dwordx4 v[8:9], off
	s_add_i32 m0, s45, 0x1c000
	s_nop 0
	global_load_lds_dwordx4 v4, s[2:3]
	v_lshl_add_u64 v[8:9], s[2:3], 0, v[0:1]
	s_add_i32 m0, s45, 0x1e000
	s_sext_i32_i8 s7, s0
	global_load_lds_dwordx4 v[8:9], off
	v_and_b32_e32 v8, 15, v16
	v_readlane_b32 s0, v247, 6
	v_and_b32_e32 v11, 48, v16
	v_lshrrev_b32_e32 v9, 6, v16
	v_or_b32_e32 v14, s0, v8
	v_lshlrev_b32_e32 v10, 6, v14
	s_movk_i32 s0, 0x3c0
	v_and_or_b32 v10, v10, s0, v11
	v_readlane_b32 s0, v247, 8
	v_lshlrev_b32_e32 v13, 2, v14
	v_and_b32_e32 v13, 32, v13
	v_lshl_add_u32 v12, v9, 10, s0
	v_bitop3_b32 v13, v10, v12, v13 bitop3:0xde
	v_readlane_b32 s0, v247, 10
	v_lshlrev_b32_e32 v10, 2, v16
	v_lshl_or_b32 v8, v8, 6, v11
	v_add_lshl_u32 v9, v9, s0, 10
	v_and_b32_e32 v10, 32, v10
	v_bitop3_b32 v15, v8, v9, v10 bitop3:0xde
	v_lshrrev_b32_e32 v8, 2, v16
	s_waitcnt vmcnt(6)
	v_and_b32_e32 v8, 28, v8
	v_readlane_b32 s0, v247, 9
	s_add_i32 s57, 0, 0x10000
	s_add_i32 s58, 0, 0x14000
	v_add_u32_e32 v12, s0, v8
	s_ashr_i32 s54, s76, 31
	s_mov_b32 s55, s76
	s_add_i32 s56, s80, s76
	v_mov_b64_e32 v[8:9], 0x80
	v_mov_b64_e32 v[10:11], 0x7f
	v_add_u32_e32 v16, s57, v15
	v_add_u32_e32 v17, s58, v15
	v_add_u32_e32 v18, 0, v13
	s_mov_b64 s[8:9], 0x100
	s_mov_b64 s[10:11], 0x180
	v_lshlrev_b32_e32 v12, 2, v12
	v_mov_b32_e32 v13, v5
	s_mov_b64 s[12:13], 0xc000
	s_mov_b64 s[14:15], 0x20000
	s_mov_b32 s59, 0x20000
	s_mov_b64 s[16:17], 0x24000
	s_mov_b32 s60, 0x24000
	s_mov_b64 s[18:19], 0x28000
	s_mov_b32 s61, 0x28000
	s_mov_b64 s[20:21], 0x2c000
	s_mov_b64 s[24:25], s[80:81]
	s_barrier
	s_branch .LBB0_366
	s_nop 0
	s_nop 0
